# v22 + FFN-up epilogue without the scalar pointer load (edge buffer address derived from the output pointer), first weight reads hoisted
# speedup vs baseline: 1.0200x; 1.0038x over previous
; #define LAS __attribute__((address_space(3)))
; #define EPI_LANE() const int lane2 = fresh_lane(), fr = lane2 & 15, fq = lane2 >> 4
;     __device__ __forceinline__ void operator()(const f32x4 (&acc)[2][2][4][2], const Unit& u) const {
;     ...
;             EPI_LANE();
;             const float* cw = P->in[24] + (size_t)layer * 3 * F2; const float* cb = P->in[25] + (size_t)layer * F2;
;             bf16_t* eb = (bf16_t*)(P->ws + WS_EB);
;             const int ch0 = u.pn * 128 + wc * 32 + 8 * fq;
;             const float m0 = fr == 0 ? 1.f : 0.f, n0 = 1.f - m0, m15 = fr == 15 ? 1.f : 0.f, n15 = 1.f - m15;
;             LAS unsigned char* wl = lds + LDS_CW + wid * 1024;
;             { const int a_ = lane2 >> 3, q4 = (lane2 & 7) * 4;
;               const float* src = (a_ < 6 ? cw + (a_ >> 1) * F2 : cb) + (a_ & 1) * F + (unsigned)(u.pn * 128 + wc * 32 + q4);
;               const f32x4 wv = *(const f32x4*)src;
;               *(LAS f32x4*)(wl + lane2 * 16) = wv; }
;             asm volatile("s_waitcnt lgkmcnt(0)" ::: "memory");
; #pragma unroll
;             for (int ai = 0; ai < 2; ++ai) {
;                 const int rowb = u.pm * BM + ai * HALF + wr * 64, q = rowb >> 6;
;                 unsigned gq[4][4], pe[2][2][4];
; #pragma unroll
;                 for (int n = 0; n < 2; ++n) {
;                     f32x4 W[2][4];
; #pragma unroll
;                     for (int part = 0; part < 2; ++part)
; #pragma unroll
;                         for (int k = 0; k < 4; ++k) W[part][k] = *(const LAS f32x4*)(wl + (k * 2 + part) * 128 + (8 * fq + 4 * n) * 4);
; #pragma unroll
;                     for (int ep = 0; ep < 2; ++ep) {
;                         f32x2 cres[2][4];
; #pragma unroll
;                         for (int part = 0; part < 2; ++part) {
;                             const f32x2 w0 = (f32x2){W[part][0][2 * ep], W[part][0][2 * ep + 1]}, w1 = (f32x2){W[part][1][2 * ep], W[part][1][2 * ep + 1]};
;                             const f32x2 w2 = (f32x2){W[part][2][2 * ep], W[part][2][2 * ep + 1]}, bb = (f32x2){W[part][3][2 * ep], W[part][3][2 * ep + 1]};
;                             const f32x2 w0a = w0 * n0, w0b = w0 * m0, w2a = w2 * n15, w2b = w2 * m15;
;                             f32x2 X[4], R[4], L[4];
; #pragma unroll
;                             for (int m = 0; m < 4; ++m) { X[m] = (f32x2){acc[ai][part][m][n][2 * ep], acc[ai][part][m][n][2 * ep + 1]};
.LBB0_346:
	s_and_b64 vcc, exec, s[10:11]
	s_cbranch_vccz .LBB0_373
	s_cmp_eq_u32 s24, 3
	s_mov_b64 s[8:9], -1
	s_cbranch_scc0 .LBB0_373
	v_mbcnt_lo_u32_b32 v130, -1, 0
	v_mbcnt_hi_u32_b32 v130, -1, v130
	v_readlane_b32 s3, v255, 12
	v_and_b32_e32 v131, 15, v130
	v_lshrrev_b32_e32 v129, 4, v130
	v_mov_b32_e32 v134, 0xbdd2d3e8
	v_mov_b32_e32 v135, 0xbdd2d3e8
	v_mov_b32_e32 v136, 0xc0135761
	v_mov_b32_e32 v137, 0xc0135761
	v_lshl_add_u32 v132, v129, 5, s3
	ds_read_b64 v[202:203], v132 offset:0
	ds_read_b64 v[204:205], v132 offset:128
	ds_read_b64 v[206:207], v132 offset:256
	ds_read_b64 v[208:209], v132 offset:384
	ds_read_b64 v[210:211], v132 offset:512
	ds_read_b64 v[212:213], v132 offset:640
	ds_read_b64 v[214:215], v132 offset:768
	ds_read_b64 v[216:217], v132 offset:896
	v_cmp_eq_u32_e64 s[6:7], 0, v131
	v_cmp_eq_u32_e64 s[8:9], 15, v131
	v_cmp_ne_u32_e64 s[56:57], 0, v131
	v_cmp_ne_u32_e64 s[58:59], 15, v131
	s_lshl_b32 s1, s72, 7
	s_or_b32 s1, s1, s49
	v_lshl_add_u32 v133, v129, 3, s1
	s_lshl_b32 s1, s73, 8
	s_add_i32 s1, s1, s33
	v_lshl_add_u32 v128, v131, 2, s1
	v_mul_lo_u32 v128, v128, s78
	v_lshl_add_u32 v128, v133, 1, v128
	s_lshl_b32 s1, s73, 2
	s_lshr_b32 s3, s33, 6
	s_add_i32 s1, s1, s3
	s_mul_i32 s1, s1, 0x2c0
	v_lshrrev_b32_e32 v129, 3, v133
	v_add_lshl_u32 v129, v129, s1, 6
	v_add_u32_e32 v162, 0x5800, v129
	s_sub_u32 s10, s52, 0x5000000
	s_subb_u32 s11, s53, 0
	s_waitcnt lgkmcnt(0)
	v_pk_fma_f32 v[234:235], v[116:117], v[206:207], v[214:215]
	v_pk_fma_f32 v[236:237], v[100:101], v[206:207], v[214:215]
	v_pk_fma_f32 v[238:239], v[84:85], v[206:207], v[214:215]
	v_pk_fma_f32 v[240:241], v[52:53], v[206:207], v[214:215]
	v_pk_fma_f32 v[236:237], v[116:117], v[202:203], v[236:237]
	v_pk_fma_f32 v[238:239], v[100:101], v[202:203], v[238:239]
	v_pk_fma_f32 v[240:241], v[84:85], v[202:203], v[240:241]
	v_fmac_f32_dpp v234, v52, v202 row_shr:1 row_mask:0xf bank_mask:0xf bound_ctrl:1
	v_fmac_f32_dpp v235, v53, v203 row_shr:1 row_mask:0xf bank_mask:0xf bound_ctrl:1
	v_pk_fma_f32 v[236:237], v[84:85], v[210:211], v[236:237]
	v_pk_fma_f32 v[238:239], v[52:53], v[210:211], v[238:239]
	v_pk_fma_f32 v[234:235], v[100:101], v[210:211], v[234:235]
	v_fmac_f32_dpp v240, v116, v210 row_shl:1 row_mask:0xf bank_mask:0xf bound_ctrl:1
	v_fmac_f32_dpp v241, v117, v211 row_shl:1 row_mask:0xf bank_mask:0xf bound_ctrl:1
	v_cvt_pk_bf16_f32 v184, v234, v235
	v_cvt_pk_bf16_f32 v192, v240, v241
	v_pk_fma_f32 v[242:243], v[124:125], v[208:209], v[216:217]
	v_pk_fma_f32 v[244:245], v[108:109], v[208:209], v[216:217]
	v_pk_fma_f32 v[246:247], v[92:93], v[208:209], v[216:217]
	v_pk_fma_f32 v[248:249], v[68:69], v[208:209], v[216:217]
	v_pk_fma_f32 v[244:245], v[124:125], v[204:205], v[244:245]
	v_pk_fma_f32 v[246:247], v[108:109], v[204:205], v[246:247]
	v_pk_fma_f32 v[248:249], v[92:93], v[204:205], v[248:249]
	v_fmac_f32_dpp v242, v68, v204 row_shr:1 row_mask:0xf bank_mask:0xf bound_ctrl:1
	v_fmac_f32_dpp v243, v69, v205 row_shr:1 row_mask:0xf bank_mask:0xf bound_ctrl:1
	v_pk_fma_f32 v[244:245], v[92:93], v[212:213], v[244:245]
	v_pk_fma_f32 v[246:247], v[68:69], v[212:213], v[246:247]
	v_pk_fma_f32 v[242:243], v[108:109], v[212:213], v[242:243]
	v_fmac_f32_dpp v248, v124, v212 row_shl:1 row_mask:0xf bank_mask:0xf bound_ctrl:1
	v_fmac_f32_dpp v249, v125, v213 row_shl:1 row_mask:0xf bank_mask:0xf bound_ctrl:1
	v_cvt_pk_bf16_f32 v188, v242, v243
	v_cvt_pk_bf16_f32 v154, v248, v249
	ds_read_b64 v[202:203], v132 offset:8
	ds_read_b64 v[204:205], v132 offset:136
	ds_read_b64 v[206:207], v132 offset:264
	ds_read_b64 v[208:209], v132 offset:392
	ds_read_b64 v[210:211], v132 offset:520
	ds_read_b64 v[212:213], v132 offset:648
	ds_read_b64 v[214:215], v132 offset:776
	ds_read_b64 v[216:217], v132 offset:904
	v_pk_mul_f32 v[138:139], v[234:235], v[234:235]
	v_pk_mul_f32 v[140:141], v[236:237], v[236:237]
	v_pk_mul_f32 v[142:143], v[238:239], v[238:239]
	v_pk_mul_f32 v[144:145], v[240:241], v[240:241]
	v_pk_fma_f32 v[138:139], v[138:139], v[134:135], v[136:137]
	v_pk_fma_f32 v[140:141], v[140:141], v[134:135], v[136:137]
	v_pk_fma_f32 v[142:143], v[142:143], v[134:135], v[136:137]
	v_pk_fma_f32 v[144:145], v[144:145], v[134:135], v[136:137]
	v_pk_mul_f32 v[138:139], v[234:235], v[138:139]
	v_pk_mul_f32 v[140:141], v[236:237], v[140:141]
	v_pk_mul_f32 v[142:143], v[238:239], v[142:143]
	v_pk_mul_f32 v[144:145], v[240:241], v[144:145]
	v_exp_f32_e32 v138, v138
	v_exp_f32_e32 v139, v139
	v_exp_f32_e32 v140, v140
	v_exp_f32_e32 v141, v141
	v_exp_f32_e32 v142, v142
	v_exp_f32_e32 v143, v143
	v_exp_f32_e32 v144, v144
	v_exp_f32_e32 v145, v145
	v_pk_mul_f32 v[146:147], v[234:235], v[242:243]
	v_pk_mul_f32 v[148:149], v[236:237], v[244:245]
	v_pk_mul_f32 v[150:151], v[238:239], v[246:247]
	v_pk_mul_f32 v[152:153], v[240:241], v[248:249]
	v_pk_add_f32 v[138:139], v[138:139], 1.0 op_sel_hi:[1,0]
	v_pk_add_f32 v[140:141], v[140:141], 1.0 op_sel_hi:[1,0]
	v_pk_add_f32 v[142:143], v[142:143], 1.0 op_sel_hi:[1,0]
	v_pk_add_f32 v[144:145], v[144:145], 1.0 op_sel_hi:[1,0]
	v_rcp_f32_e32 v138, v138
	v_rcp_f32_e32 v139, v139
	v_rcp_f32_e32 v140, v140
	v_rcp_f32_e32 v141, v141
	v_rcp_f32_e32 v142, v142
	v_rcp_f32_e32 v143, v143
	v_rcp_f32_e32 v144, v144
	v_rcp_f32_e32 v145, v145
	v_pk_mul_f32 v[146:147], v[146:147], v[138:139]
	v_pk_mul_f32 v[148:149], v[148:149], v[140:141]
	v_pk_mul_f32 v[150:151], v[150:151], v[142:143]
	v_pk_mul_f32 v[152:153], v[152:153], v[144:145]
	v_cvt_pk_bf16_f32 v218, v146, v147
	v_cvt_pk_bf16_f32 v222, v148, v149
	v_cvt_pk_bf16_f32 v226, v150, v151
	v_cvt_pk_bf16_f32 v230, v152, v153
	s_waitcnt lgkmcnt(0)
;     __device__ __forceinline__ void operator()(const f32x4 (&acc)[2][2][4][2], const Unit& u) const {
;     ...
;                     for (int ep = 0; ep < 2; ++ep) {
;                         f32x2 cres[2][4];
; #pragma unroll
;                         for (int part = 0; part < 2; ++part) {
;                             const f32x2 w0 = (f32x2){W[part][0][2 * ep], W[part][0][2 * ep + 1]}, w1 = (f32x2){W[part][1][2 * ep], W[part][1][2 * ep + 1]};
;                             const f32x2 w2 = (f32x2){W[part][2][2 * ep], W[part][2][2 * ep + 1]}, bb = (f32x2){W[part][3][2 * ep], W[part][3][2 * ep + 1]};
;                             const f32x2 w0a = w0 * n0, w0b = w0 * m0, w2a = w2 * n15, w2b = w2 * m15;
;                             f32x2 X[4], R[4], L[4];
; #pragma unroll
;                             for (int m = 0; m < 4; ++m) { X[m] = (f32x2){acc[ai][part][m][n][2 * ep], acc[ai][part][m][n][2 * ep + 1]};
;                                 R[m] = (f32x2){dpp_prev(X[m].x), dpp_prev(X[m].y)}; L[m] = (f32x2){dpp_next(X[m].x), dpp_next(X[m].y)}; }
; #pragma unroll
;                             for (int m = 0; m < 4; ++m) {
;                                 f32x2 c = X[m] * w1 + bb; c = R[m] * w0a + c; c = L[m] * w2a + c;
;                                 if (m > 0) c = R[m > 0 ? m - 1 : 0] * w0b + c;
;                                 if (m < 3) c = L[m < 3 ? m + 1 : 3] * w2b + c;
;                                 cres[part][m] = c;
;                             }
;                             pe[0][part][n * 2 + ep] = cvt_pk_bf16(cres[part][0].x, cres[part][0].y);
;                             pe[1][part][n * 2 + ep] = cvt_pk_bf16(cres[part][3].x, cres[part][3].y);
;                             __builtin_amdgcn_sched_barrier(0);
;                         }
; #pragma unroll
;                         for (int m = 0; m < 4; ++m) {
;                             const f32x2 a = cres[0][m], v = cres[1][m];
;                             const f32x2 t = (a * a) * (-0.10294324f) + (-2.3022082f), z = a * t;
;                             f32x2 d; d.x = __builtin_amdgcn_exp2f(z.x) + 1.f; d.y = __builtin_amdgcn_exp2f(z.y) + 1.f;
;                             f32x2 r; r.x = __builtin_amdgcn_rcpf(d.x); r.y = __builtin_amdgcn_rcpf(d.y);
;                             const f32x2 o = (a * v) * r;
;                             gq[m][n * 2 + ep] = cvt_pk_bf16(o.x, o.y);
	v_pk_fma_f32 v[234:235], v[118:119], v[206:207], v[214:215]
	v_pk_fma_f32 v[236:237], v[102:103], v[206:207], v[214:215]
	v_pk_fma_f32 v[238:239], v[86:87], v[206:207], v[214:215]
	v_pk_fma_f32 v[240:241], v[54:55], v[206:207], v[214:215]
	v_pk_fma_f32 v[236:237], v[118:119], v[202:203], v[236:237]
	v_pk_fma_f32 v[238:239], v[102:103], v[202:203], v[238:239]
	v_pk_fma_f32 v[240:241], v[86:87], v[202:203], v[240:241]
	v_fmac_f32_dpp v234, v54, v202 row_shr:1 row_mask:0xf bank_mask:0xf bound_ctrl:1
	v_fmac_f32_dpp v235, v55, v203 row_shr:1 row_mask:0xf bank_mask:0xf bound_ctrl:1
	v_pk_fma_f32 v[236:237], v[86:87], v[210:211], v[236:237]
	v_pk_fma_f32 v[238:239], v[54:55], v[210:211], v[238:239]
	v_pk_fma_f32 v[234:235], v[102:103], v[210:211], v[234:235]
	v_fmac_f32_dpp v240, v118, v210 row_shl:1 row_mask:0xf bank_mask:0xf bound_ctrl:1
	v_fmac_f32_dpp v241, v119, v211 row_shl:1 row_mask:0xf bank_mask:0xf bound_ctrl:1
	v_cvt_pk_bf16_f32 v185, v234, v235
	v_cvt_pk_bf16_f32 v193, v240, v241
	v_pk_fma_f32 v[242:243], v[126:127], v[208:209], v[216:217]
	v_pk_fma_f32 v[244:245], v[110:111], v[208:209], v[216:217]
	v_pk_fma_f32 v[246:247], v[94:95], v[208:209], v[216:217]
	v_pk_fma_f32 v[248:249], v[70:71], v[208:209], v[216:217]
	v_pk_fma_f32 v[244:245], v[126:127], v[204:205], v[244:245]
	v_pk_fma_f32 v[246:247], v[110:111], v[204:205], v[246:247]
	v_pk_fma_f32 v[248:249], v[94:95], v[204:205], v[248:249]
	v_fmac_f32_dpp v242, v70, v204 row_shr:1 row_mask:0xf bank_mask:0xf bound_ctrl:1
	v_fmac_f32_dpp v243, v71, v205 row_shr:1 row_mask:0xf bank_mask:0xf bound_ctrl:1
	v_pk_fma_f32 v[244:245], v[94:95], v[212:213], v[244:245]
	v_pk_fma_f32 v[246:247], v[70:71], v[212:213], v[246:247]
	v_pk_fma_f32 v[242:243], v[110:111], v[212:213], v[242:243]
	v_fmac_f32_dpp v248, v126, v212 row_shl:1 row_mask:0xf bank_mask:0xf bound_ctrl:1
	v_fmac_f32_dpp v249, v127, v213 row_shl:1 row_mask:0xf bank_mask:0xf bound_ctrl:1
	v_cvt_pk_bf16_f32 v189, v242, v243
	v_cvt_pk_bf16_f32 v155, v248, v249
	ds_read_b64 v[202:203], v132 offset:16
	ds_read_b64 v[204:205], v132 offset:144
	ds_read_b64 v[206:207], v132 offset:272
	ds_read_b64 v[208:209], v132 offset:400
	ds_read_b64 v[210:211], v132 offset:528
	ds_read_b64 v[212:213], v132 offset:656
	ds_read_b64 v[214:215], v132 offset:784
	ds_read_b64 v[216:217], v132 offset:912
	v_pk_mul_f32 v[138:139], v[234:235], v[234:235]
	v_pk_mul_f32 v[140:141], v[236:237], v[236:237]
	v_pk_mul_f32 v[142:143], v[238:239], v[238:239]
	v_pk_mul_f32 v[144:145], v[240:241], v[240:241]
	v_pk_fma_f32 v[138:139], v[138:139], v[134:135], v[136:137]
	v_pk_fma_f32 v[140:141], v[140:141], v[134:135], v[136:137]
	v_pk_fma_f32 v[142:143], v[142:143], v[134:135], v[136:137]
	v_pk_fma_f32 v[144:145], v[144:145], v[134:135], v[136:137]
	v_pk_mul_f32 v[138:139], v[234:235], v[138:139]
	v_pk_mul_f32 v[140:141], v[236:237], v[140:141]
	v_pk_mul_f32 v[142:143], v[238:239], v[142:143]
	v_pk_mul_f32 v[144:145], v[240:241], v[144:145]
	v_exp_f32_e32 v138, v138
	v_exp_f32_e32 v139, v139
	v_exp_f32_e32 v140, v140
	v_exp_f32_e32 v141, v141
	v_exp_f32_e32 v142, v142
	v_exp_f32_e32 v143, v143
	v_exp_f32_e32 v144, v144
	v_exp_f32_e32 v145, v145
	v_pk_mul_f32 v[146:147], v[234:235], v[242:243]
	v_pk_mul_f32 v[148:149], v[236:237], v[244:245]
	v_pk_mul_f32 v[150:151], v[238:239], v[246:247]
	v_pk_mul_f32 v[152:153], v[240:241], v[248:249]
	v_pk_add_f32 v[138:139], v[138:139], 1.0 op_sel_hi:[1,0]
	v_pk_add_f32 v[140:141], v[140:141], 1.0 op_sel_hi:[1,0]
	v_pk_add_f32 v[142:143], v[142:143], 1.0 op_sel_hi:[1,0]
	v_pk_add_f32 v[144:145], v[144:145], 1.0 op_sel_hi:[1,0]
	v_rcp_f32_e32 v138, v138
	v_rcp_f32_e32 v139, v139
	v_rcp_f32_e32 v140, v140
	v_rcp_f32_e32 v141, v141
	v_rcp_f32_e32 v142, v142
	v_rcp_f32_e32 v143, v143
	v_rcp_f32_e32 v144, v144
	v_rcp_f32_e32 v145, v145
	v_pk_mul_f32 v[146:147], v[146:147], v[138:139]
	v_pk_mul_f32 v[148:149], v[148:149], v[140:141]
	v_pk_mul_f32 v[150:151], v[150:151], v[142:143]
	v_pk_mul_f32 v[152:153], v[152:153], v[144:145]
	v_cvt_pk_bf16_f32 v219, v146, v147
	v_cvt_pk_bf16_f32 v223, v148, v149
	v_cvt_pk_bf16_f32 v227, v150, v151
	v_cvt_pk_bf16_f32 v231, v152, v153
	s_waitcnt lgkmcnt(0)
	v_pk_fma_f32 v[234:235], v[112:113], v[206:207], v[214:215]
	v_pk_fma_f32 v[236:237], v[96:97], v[206:207], v[214:215]
	v_pk_fma_f32 v[238:239], v[80:81], v[206:207], v[214:215]
	v_pk_fma_f32 v[240:241], v[48:49], v[206:207], v[214:215]
	v_pk_fma_f32 v[236:237], v[112:113], v[202:203], v[236:237]
	v_pk_fma_f32 v[238:239], v[96:97], v[202:203], v[238:239]
	v_pk_fma_f32 v[240:241], v[80:81], v[202:203], v[240:241]
	v_fmac_f32_dpp v234, v48, v202 row_shr:1 row_mask:0xf bank_mask:0xf bound_ctrl:1
	v_fmac_f32_dpp v235, v49, v203 row_shr:1 row_mask:0xf bank_mask:0xf bound_ctrl:1
	v_pk_fma_f32 v[236:237], v[80:81], v[210:211], v[236:237]
	v_pk_fma_f32 v[238:239], v[48:49], v[210:211], v[238:239]
	v_pk_fma_f32 v[234:235], v[96:97], v[210:211], v[234:235]
	v_fmac_f32_dpp v240, v112, v210 row_shl:1 row_mask:0xf bank_mask:0xf bound_ctrl:1
	v_fmac_f32_dpp v241, v113, v211 row_shl:1 row_mask:0xf bank_mask:0xf bound_ctrl:1
	v_cvt_pk_bf16_f32 v186, v234, v235
	v_cvt_pk_bf16_f32 v194, v240, v241
	v_pk_fma_f32 v[242:243], v[120:121], v[208:209], v[216:217]
	v_pk_fma_f32 v[244:245], v[104:105], v[208:209], v[216:217]
	v_pk_fma_f32 v[246:247], v[88:89], v[208:209], v[216:217]
	v_pk_fma_f32 v[248:249], v[60:61], v[208:209], v[216:217]
	v_pk_fma_f32 v[244:245], v[120:121], v[204:205], v[244:245]
	v_pk_fma_f32 v[246:247], v[104:105], v[204:205], v[246:247]
	v_pk_fma_f32 v[248:249], v[88:89], v[204:205], v[248:249]
	v_fmac_f32_dpp v242, v60, v204 row_shr:1 row_mask:0xf bank_mask:0xf bound_ctrl:1
;     __device__ __forceinline__ void operator()(const f32x4 (&acc)[2][2][4][2], const Unit& u) const {
;     ...
;                     for (int ep = 0; ep < 2; ++ep) {
;                         f32x2 cres[2][4];
; #pragma unroll
;                         for (int part = 0; part < 2; ++part) {
;                             const f32x2 w0 = (f32x2){W[part][0][2 * ep], W[part][0][2 * ep + 1]}, w1 = (f32x2){W[part][1][2 * ep], W[part][1][2 * ep + 1]};
;                             const f32x2 w2 = (f32x2){W[part][2][2 * ep], W[part][2][2 * ep + 1]}, bb = (f32x2){W[part][3][2 * ep], W[part][3][2 * ep + 1]};
;                             const f32x2 w0a = w0 * n0, w0b = w0 * m0, w2a = w2 * n15, w2b = w2 * m15;
;                             f32x2 X[4], R[4], L[4];
; #pragma unroll
;                             for (int m = 0; m < 4; ++m) { X[m] = (f32x2){acc[ai][part][m][n][2 * ep], acc[ai][part][m][n][2 * ep + 1]};
;                                 R[m] = (f32x2){dpp_prev(X[m].x), dpp_prev(X[m].y)}; L[m] = (f32x2){dpp_next(X[m].x), dpp_next(X[m].y)}; }
; #pragma unroll
;                             for (int m = 0; m < 4; ++m) {
;                                 f32x2 c = X[m] * w1 + bb; c = R[m] * w0a + c; c = L[m] * w2a + c;
;                                 if (m > 0) c = R[m > 0 ? m - 1 : 0] * w0b + c;
;                                 if (m < 3) c = L[m < 3 ? m + 1 : 3] * w2b + c;
;                                 cres[part][m] = c;
;                             }
;                             pe[0][part][n * 2 + ep] = cvt_pk_bf16(cres[part][0].x, cres[part][0].y);
;                             pe[1][part][n * 2 + ep] = cvt_pk_bf16(cres[part][3].x, cres[part][3].y);
;                             __builtin_amdgcn_sched_barrier(0);
;                         }
; #pragma unroll
;                         for (int m = 0; m < 4; ++m) {
;                             const f32x2 a = cres[0][m], v = cres[1][m];
;                             const f32x2 t = (a * a) * (-0.10294324f) + (-2.3022082f), z = a * t;
;                             f32x2 d; d.x = __builtin_amdgcn_exp2f(z.x) + 1.f; d.y = __builtin_amdgcn_exp2f(z.y) + 1.f;
;                             f32x2 r; r.x = __builtin_amdgcn_rcpf(d.x); r.y = __builtin_amdgcn_rcpf(d.y);
;                             const f32x2 o = (a * v) * r;
;                             gq[m][n * 2 + ep] = cvt_pk_bf16(o.x, o.y);
	v_fmac_f32_dpp v243, v61, v205 row_shr:1 row_mask:0xf bank_mask:0xf bound_ctrl:1
	v_pk_fma_f32 v[244:245], v[88:89], v[212:213], v[244:245]
	v_pk_fma_f32 v[246:247], v[60:61], v[212:213], v[246:247]
	v_pk_fma_f32 v[242:243], v[104:105], v[212:213], v[242:243]
	v_fmac_f32_dpp v248, v120, v212 row_shl:1 row_mask:0xf bank_mask:0xf bound_ctrl:1
	v_fmac_f32_dpp v249, v121, v213 row_shl:1 row_mask:0xf bank_mask:0xf bound_ctrl:1
	v_cvt_pk_bf16_f32 v190, v242, v243
	v_cvt_pk_bf16_f32 v156, v248, v249
	ds_read_b64 v[202:203], v132 offset:24
	ds_read_b64 v[204:205], v132 offset:152
	ds_read_b64 v[206:207], v132 offset:280
	ds_read_b64 v[208:209], v132 offset:408
	ds_read_b64 v[210:211], v132 offset:536
	ds_read_b64 v[212:213], v132 offset:664
	ds_read_b64 v[214:215], v132 offset:792
	ds_read_b64 v[216:217], v132 offset:920
	v_pk_mul_f32 v[138:139], v[234:235], v[234:235]
	v_pk_mul_f32 v[140:141], v[236:237], v[236:237]
	v_pk_mul_f32 v[142:143], v[238:239], v[238:239]
	v_pk_mul_f32 v[144:145], v[240:241], v[240:241]
	v_pk_fma_f32 v[138:139], v[138:139], v[134:135], v[136:137]
	v_pk_fma_f32 v[140:141], v[140:141], v[134:135], v[136:137]
	v_pk_fma_f32 v[142:143], v[142:143], v[134:135], v[136:137]
	v_pk_fma_f32 v[144:145], v[144:145], v[134:135], v[136:137]
	v_pk_mul_f32 v[138:139], v[234:235], v[138:139]
	v_pk_mul_f32 v[140:141], v[236:237], v[140:141]
	v_pk_mul_f32 v[142:143], v[238:239], v[142:143]
	v_pk_mul_f32 v[144:145], v[240:241], v[144:145]
	v_exp_f32_e32 v138, v138
	v_exp_f32_e32 v139, v139
	v_exp_f32_e32 v140, v140
	v_exp_f32_e32 v141, v141
	v_exp_f32_e32 v142, v142
	v_exp_f32_e32 v143, v143
	v_exp_f32_e32 v144, v144
	v_exp_f32_e32 v145, v145
	v_pk_mul_f32 v[146:147], v[234:235], v[242:243]
	v_pk_mul_f32 v[148:149], v[236:237], v[244:245]
	v_pk_mul_f32 v[150:151], v[238:239], v[246:247]
	v_pk_mul_f32 v[152:153], v[240:241], v[248:249]
	v_pk_add_f32 v[138:139], v[138:139], 1.0 op_sel_hi:[1,0]
	v_pk_add_f32 v[140:141], v[140:141], 1.0 op_sel_hi:[1,0]
	v_pk_add_f32 v[142:143], v[142:143], 1.0 op_sel_hi:[1,0]
	v_pk_add_f32 v[144:145], v[144:145], 1.0 op_sel_hi:[1,0]
	v_rcp_f32_e32 v138, v138
	v_rcp_f32_e32 v139, v139
	v_rcp_f32_e32 v140, v140
	v_rcp_f32_e32 v141, v141
	v_rcp_f32_e32 v142, v142
	v_rcp_f32_e32 v143, v143
	v_rcp_f32_e32 v144, v144
	v_rcp_f32_e32 v145, v145
	v_pk_mul_f32 v[146:147], v[146:147], v[138:139]
	v_pk_mul_f32 v[148:149], v[148:149], v[140:141]
	v_pk_mul_f32 v[150:151], v[150:151], v[142:143]
	v_pk_mul_f32 v[152:153], v[152:153], v[144:145]
	v_cvt_pk_bf16_f32 v220, v146, v147
	v_cvt_pk_bf16_f32 v224, v148, v149
	v_cvt_pk_bf16_f32 v228, v150, v151
	v_cvt_pk_bf16_f32 v232, v152, v153
	s_waitcnt lgkmcnt(0)
	v_pk_fma_f32 v[234:235], v[114:115], v[206:207], v[214:215]
	v_pk_fma_f32 v[236:237], v[98:99], v[206:207], v[214:215]
	v_pk_fma_f32 v[238:239], v[82:83], v[206:207], v[214:215]
	v_pk_fma_f32 v[240:241], v[50:51], v[206:207], v[214:215]
	v_pk_fma_f32 v[236:237], v[114:115], v[202:203], v[236:237]
	v_pk_fma_f32 v[238:239], v[98:99], v[202:203], v[238:239]
	v_pk_fma_f32 v[240:241], v[82:83], v[202:203], v[240:241]
	v_fmac_f32_dpp v234, v50, v202 row_shr:1 row_mask:0xf bank_mask:0xf bound_ctrl:1
	v_fmac_f32_dpp v235, v51, v203 row_shr:1 row_mask:0xf bank_mask:0xf bound_ctrl:1
	v_pk_fma_f32 v[236:237], v[82:83], v[210:211], v[236:237]
	v_pk_fma_f32 v[238:239], v[50:51], v[210:211], v[238:239]
	v_pk_fma_f32 v[234:235], v[98:99], v[210:211], v[234:235]
	v_fmac_f32_dpp v240, v114, v210 row_shl:1 row_mask:0xf bank_mask:0xf bound_ctrl:1
	v_fmac_f32_dpp v241, v115, v211 row_shl:1 row_mask:0xf bank_mask:0xf bound_ctrl:1
	v_cvt_pk_bf16_f32 v187, v234, v235
	v_cvt_pk_bf16_f32 v195, v240, v241
	v_pk_fma_f32 v[242:243], v[122:123], v[208:209], v[216:217]
	v_pk_fma_f32 v[244:245], v[106:107], v[208:209], v[216:217]
	v_pk_fma_f32 v[246:247], v[90:91], v[208:209], v[216:217]
	v_pk_fma_f32 v[248:249], v[62:63], v[208:209], v[216:217]
	v_pk_fma_f32 v[244:245], v[122:123], v[204:205], v[244:245]
	v_pk_fma_f32 v[246:247], v[106:107], v[204:205], v[246:247]
	v_pk_fma_f32 v[248:249], v[90:91], v[204:205], v[248:249]
	v_fmac_f32_dpp v242, v62, v204 row_shr:1 row_mask:0xf bank_mask:0xf bound_ctrl:1
	v_fmac_f32_dpp v243, v63, v205 row_shr:1 row_mask:0xf bank_mask:0xf bound_ctrl:1
	v_pk_fma_f32 v[244:245], v[90:91], v[212:213], v[244:245]
	v_pk_fma_f32 v[246:247], v[62:63], v[212:213], v[246:247]
	v_pk_fma_f32 v[242:243], v[106:107], v[212:213], v[242:243]
	v_fmac_f32_dpp v248, v122, v212 row_shl:1 row_mask:0xf bank_mask:0xf bound_ctrl:1
	v_fmac_f32_dpp v249, v123, v213 row_shl:1 row_mask:0xf bank_mask:0xf bound_ctrl:1
	v_cvt_pk_bf16_f32 v191, v242, v243
	v_cvt_pk_bf16_f32 v157, v248, v249
	ds_read_b64 v[202:203], v132 offset:0
	ds_read_b64 v[204:205], v132 offset:128
	ds_read_b64 v[206:207], v132 offset:256
	ds_read_b64 v[208:209], v132 offset:384
	ds_read_b64 v[210:211], v132 offset:512
	ds_read_b64 v[212:213], v132 offset:640
	ds_read_b64 v[214:215], v132 offset:768
	ds_read_b64 v[216:217], v132 offset:896
	v_pk_mul_f32 v[138:139], v[234:235], v[234:235]
	v_pk_mul_f32 v[140:141], v[236:237], v[236:237]
	v_pk_mul_f32 v[142:143], v[238:239], v[238:239]
	v_pk_mul_f32 v[144:145], v[240:241], v[240:241]
	v_pk_fma_f32 v[138:139], v[138:139], v[134:135], v[136:137]
	v_pk_fma_f32 v[140:141], v[140:141], v[134:135], v[136:137]
	v_pk_fma_f32 v[142:143], v[142:143], v[134:135], v[136:137]
	v_pk_fma_f32 v[144:145], v[144:145], v[134:135], v[136:137]
	v_pk_mul_f32 v[138:139], v[234:235], v[138:139]
	v_pk_mul_f32 v[140:141], v[236:237], v[140:141]
	v_pk_mul_f32 v[142:143], v[238:239], v[142:143]
	v_pk_mul_f32 v[144:145], v[240:241], v[144:145]
; __device__ __forceinline__ unsigned cvt_pk_bf16(float lo, float hi) { unsigned r; asm volatile("v_cvt_pk_bf16_f32 %0, %1, %2" : "=v"(r) : "v"(lo), "v"(hi)); return r; }
;     __device__ __forceinline__ void operator()(const f32x4 (&acc)[2][2][4][2], const Unit& u) const {
;     ...
;                         for (int m = 0; m < 4; ++m) {
;                             const f32x2 a = cres[0][m], v = cres[1][m];
;                             const f32x2 t = (a * a) * (-0.10294324f) + (-2.3022082f), z = a * t;
;                             f32x2 d; d.x = __builtin_amdgcn_exp2f(z.x) + 1.f; d.y = __builtin_amdgcn_exp2f(z.y) + 1.f;
;                             f32x2 r; r.x = __builtin_amdgcn_rcpf(d.x); r.y = __builtin_amdgcn_rcpf(d.y);
;                             const f32x2 o = (a * v) * r;
;                             gq[m][n * 2 + ep] = cvt_pk_bf16(o.x, o.y);
;                         }
;                         __builtin_amdgcn_sched_barrier(0);
;                     }
;                 }
;                 if (fr == 0 || fr == 15) {
;                     const bool sel = fr == 15;
;                     bf16_t* ep_ = eb + (unsigned)((((q * 2 + (sel ? 1 : 0)) * 352 + (ch0 >> 3)) * 4) * 8);
; #pragma unroll
;                     for (int part = 0; part < 2; ++part) {
;                         float rw[8];
; #pragma unroll
;                         for (int e = 0; e < 8; ++e) rw[e] = sel ? acc[ai][part][3][e >> 2][e & 3] : acc[ai][part][0][e >> 2][e & 3];
;                         *(u32x4*)(ep_ + part * 8) = pack8(rw);
;                         *(u32x4*)(ep_ + (2 + part) * 8) = (u32x4){sel ? pe[1][part][0] : pe[0][part][0], sel ? pe[1][part][1] : pe[0][part][1], sel ? pe[1][part][2] : pe[0][part][2], sel ? pe[1][part][3] : pe[0][part][3]};
;                     }
;                 }
; #pragma unroll
;                 for (int m = 0; m < 4; ++m) {
;                     const bool edge = (m == 0 && fr == 0) || (m == 3 && fr == 15);
;                     if (!edge) *(u32x4*)((bf16_t*)O + (unsigned)((rowb + m * 16 + fr) * F + ch0)) = (u32x4){gq[m][0], gq[m][1], gq[m][2], gq[m][3]};
;                 }
	v_exp_f32_e32 v138, v138
	v_exp_f32_e32 v139, v139
	v_exp_f32_e32 v140, v140
	v_exp_f32_e32 v141, v141
	v_exp_f32_e32 v142, v142
	v_exp_f32_e32 v143, v143
	v_exp_f32_e32 v144, v144
	v_exp_f32_e32 v145, v145
	v_pk_mul_f32 v[146:147], v[234:235], v[242:243]
	v_pk_mul_f32 v[148:149], v[236:237], v[244:245]
	v_pk_mul_f32 v[150:151], v[238:239], v[246:247]
	v_pk_mul_f32 v[152:153], v[240:241], v[248:249]
	v_pk_add_f32 v[138:139], v[138:139], 1.0 op_sel_hi:[1,0]
	v_pk_add_f32 v[140:141], v[140:141], 1.0 op_sel_hi:[1,0]
	v_pk_add_f32 v[142:143], v[142:143], 1.0 op_sel_hi:[1,0]
	v_pk_add_f32 v[144:145], v[144:145], 1.0 op_sel_hi:[1,0]
	v_rcp_f32_e32 v138, v138
	v_rcp_f32_e32 v139, v139
	v_rcp_f32_e32 v140, v140
	v_rcp_f32_e32 v141, v141
	v_rcp_f32_e32 v142, v142
	v_rcp_f32_e32 v143, v143
	v_rcp_f32_e32 v144, v144
	v_rcp_f32_e32 v145, v145
	v_pk_mul_f32 v[146:147], v[146:147], v[138:139]
	v_pk_mul_f32 v[148:149], v[148:149], v[140:141]
	v_pk_mul_f32 v[150:151], v[150:151], v[142:143]
	v_pk_mul_f32 v[152:153], v[152:153], v[144:145]
	v_cvt_pk_bf16_f32 v221, v146, v147
	v_cvt_pk_bf16_f32 v225, v148, v149
	v_cvt_pk_bf16_f32 v229, v150, v151
	v_cvt_pk_bf16_f32 v233, v152, v153
	s_mov_b64 s[22:23], exec
	s_mov_b64 exec, s[6:7]
	v_cvt_pk_bf16_f32 v138, v116, v117
	v_cvt_pk_bf16_f32 v139, v118, v119
	v_cvt_pk_bf16_f32 v140, v112, v113
	v_cvt_pk_bf16_f32 v141, v114, v115
	v_cvt_pk_bf16_f32 v142, v124, v125
	v_cvt_pk_bf16_f32 v143, v126, v127
	v_cvt_pk_bf16_f32 v144, v120, v121
	v_cvt_pk_bf16_f32 v145, v122, v123
	global_store_dwordx4 v129, v[138:141], s[10:11]
	global_store_dwordx4 v129, v[142:145], s[10:11] offset:16
	global_store_dwordx4 v129, v[184:187], s[10:11] offset:32
	global_store_dwordx4 v129, v[188:191], s[10:11] offset:48
	s_mov_b64 exec, s[8:9]
	v_cvt_pk_bf16_f32 v146, v52, v53
	v_cvt_pk_bf16_f32 v147, v54, v55
	v_cvt_pk_bf16_f32 v148, v48, v49
	v_cvt_pk_bf16_f32 v149, v50, v51
	v_cvt_pk_bf16_f32 v150, v68, v69
	v_cvt_pk_bf16_f32 v151, v70, v71
	v_cvt_pk_bf16_f32 v152, v60, v61
	v_cvt_pk_bf16_f32 v153, v62, v63
	global_store_dwordx4 v162, v[146:149], s[10:11]
	global_store_dwordx4 v162, v[150:153], s[10:11] offset:16
	global_store_dwordx4 v162, v[192:195], s[10:11] offset:32
	global_store_dwordx4 v162, v[154:157], s[10:11] offset:48
	s_mov_b64 exec, s[56:57]
	global_store_dwordx4 v128, v[218:221], s[52:53]
	s_mov_b64 exec, s[22:23]
	v_add_u32_e32 v133, 0x1600, v128
	v_add_u32_e32 v130, 0x2c00, v128
	v_add_u32_e32 v131, 0x4200, v128
	global_store_dwordx4 v133, v[222:225], s[52:53]
	global_store_dwordx4 v130, v[226:229], s[52:53]
	s_mov_b64 exec, s[58:59]
	global_store_dwordx4 v131, v[230:233], s[52:53]
	s_mov_b64 exec, s[22:23]
	v_add_u32_e32 v128, 0xb0000, v128
	v_add_u32_e32 v129, 0x16000, v129
	v_add_u32_e32 v162, 0x16000, v162
	s_nop 1
	s_waitcnt lgkmcnt(0)
	v_pk_fma_f32 v[234:235], v[64:65], v[206:207], v[214:215]
	v_pk_fma_f32 v[236:237], v[36:37], v[206:207], v[214:215]
	v_pk_fma_f32 v[238:239], v[20:21], v[206:207], v[214:215]
	v_pk_fma_f32 v[240:241], v[4:5], v[206:207], v[214:215]
	v_pk_fma_f32 v[236:237], v[64:65], v[202:203], v[236:237]
	v_pk_fma_f32 v[238:239], v[36:37], v[202:203], v[238:239]
	v_pk_fma_f32 v[240:241], v[20:21], v[202:203], v[240:241]
	v_fmac_f32_dpp v234, v4, v202 row_shr:1 row_mask:0xf bank_mask:0xf bound_ctrl:1
	v_fmac_f32_dpp v235, v5, v203 row_shr:1 row_mask:0xf bank_mask:0xf bound_ctrl:1
	v_pk_fma_f32 v[236:237], v[20:21], v[210:211], v[236:237]
	v_pk_fma_f32 v[238:239], v[4:5], v[210:211], v[238:239]
	v_pk_fma_f32 v[234:235], v[36:37], v[210:211], v[234:235]
	v_fmac_f32_dpp v240, v64, v210 row_shl:1 row_mask:0xf bank_mask:0xf bound_ctrl:1
	v_fmac_f32_dpp v241, v65, v211 row_shl:1 row_mask:0xf bank_mask:0xf bound_ctrl:1
	v_cvt_pk_bf16_f32 v184, v234, v235
	v_cvt_pk_bf16_f32 v192, v240, v241
	v_pk_fma_f32 v[242:243], v[76:77], v[208:209], v[216:217]
	v_pk_fma_f32 v[244:245], v[44:45], v[208:209], v[216:217]
	v_pk_fma_f32 v[246:247], v[28:29], v[208:209], v[216:217]
	v_pk_fma_f32 v[248:249], v[12:13], v[208:209], v[216:217]
	v_pk_fma_f32 v[244:245], v[76:77], v[204:205], v[244:245]
	v_pk_fma_f32 v[246:247], v[44:45], v[204:205], v[246:247]
	v_pk_fma_f32 v[248:249], v[28:29], v[204:205], v[248:249]
	v_fmac_f32_dpp v242, v12, v204 row_shr:1 row_mask:0xf bank_mask:0xf bound_ctrl:1
	v_fmac_f32_dpp v243, v13, v205 row_shr:1 row_mask:0xf bank_mask:0xf bound_ctrl:1
	v_pk_fma_f32 v[244:245], v[28:29], v[212:213], v[244:245]
	v_pk_fma_f32 v[246:247], v[12:13], v[212:213], v[246:247]
	v_pk_fma_f32 v[242:243], v[44:45], v[212:213], v[242:243]
	v_fmac_f32_dpp v248, v76, v212 row_shl:1 row_mask:0xf bank_mask:0xf bound_ctrl:1
	v_fmac_f32_dpp v249, v77, v213 row_shl:1 row_mask:0xf bank_mask:0xf bound_ctrl:1
	v_cvt_pk_bf16_f32 v188, v242, v243
	v_cvt_pk_bf16_f32 v154, v248, v249
	ds_read_b64 v[202:203], v132 offset:8
	ds_read_b64 v[204:205], v132 offset:136
	ds_read_b64 v[206:207], v132 offset:264
	ds_read_b64 v[208:209], v132 offset:392
	ds_read_b64 v[210:211], v132 offset:520
	ds_read_b64 v[212:213], v132 offset:648
	ds_read_b64 v[214:215], v132 offset:776
	ds_read_b64 v[216:217], v132 offset:904
	v_pk_mul_f32 v[138:139], v[234:235], v[234:235]
	v_pk_mul_f32 v[140:141], v[236:237], v[236:237]
	v_pk_mul_f32 v[142:143], v[238:239], v[238:239]
	v_pk_mul_f32 v[144:145], v[240:241], v[240:241]
	v_pk_fma_f32 v[138:139], v[138:139], v[134:135], v[136:137]
	v_pk_fma_f32 v[140:141], v[140:141], v[134:135], v[136:137]
	v_pk_fma_f32 v[142:143], v[142:143], v[134:135], v[136:137]
	v_pk_fma_f32 v[144:145], v[144:145], v[134:135], v[136:137]
	v_pk_mul_f32 v[138:139], v[234:235], v[138:139]
	v_pk_mul_f32 v[140:141], v[236:237], v[140:141]
	v_pk_mul_f32 v[142:143], v[238:239], v[142:143]
	v_pk_mul_f32 v[144:145], v[240:241], v[144:145]
	v_exp_f32_e32 v138, v138
	v_exp_f32_e32 v139, v139
	v_exp_f32_e32 v140, v140
	v_exp_f32_e32 v141, v141
	v_exp_f32_e32 v142, v142
	v_exp_f32_e32 v143, v143
	v_exp_f32_e32 v144, v144
	v_exp_f32_e32 v145, v145
	v_pk_mul_f32 v[146:147], v[234:235], v[242:243]
	v_pk_mul_f32 v[148:149], v[236:237], v[244:245]
	v_pk_mul_f32 v[150:151], v[238:239], v[246:247]
	v_pk_mul_f32 v[152:153], v[240:241], v[248:249]
	v_pk_add_f32 v[138:139], v[138:139], 1.0 op_sel_hi:[1,0]
	v_pk_add_f32 v[140:141], v[140:141], 1.0 op_sel_hi:[1,0]
	v_pk_add_f32 v[142:143], v[142:143], 1.0 op_sel_hi:[1,0]
	v_pk_add_f32 v[144:145], v[144:145], 1.0 op_sel_hi:[1,0]
	v_rcp_f32_e32 v138, v138
	v_rcp_f32_e32 v139, v139
	v_rcp_f32_e32 v140, v140
	v_rcp_f32_e32 v141, v141
	v_rcp_f32_e32 v142, v142
	v_rcp_f32_e32 v143, v143
	v_rcp_f32_e32 v144, v144
	v_rcp_f32_e32 v145, v145
	v_pk_mul_f32 v[146:147], v[146:147], v[138:139]
	v_pk_mul_f32 v[148:149], v[148:149], v[140:141]
	v_pk_mul_f32 v[150:151], v[150:151], v[142:143]
	v_pk_mul_f32 v[152:153], v[152:153], v[144:145]
	v_cvt_pk_bf16_f32 v218, v146, v147
	v_cvt_pk_bf16_f32 v222, v148, v149
	v_cvt_pk_bf16_f32 v226, v150, v151
	v_cvt_pk_bf16_f32 v230, v152, v153
	s_waitcnt lgkmcnt(0)
;     __device__ __forceinline__ void operator()(const f32x4 (&acc)[2][2][4][2], const Unit& u) const {
;     ...
;                     for (int ep = 0; ep < 2; ++ep) {
;                         f32x2 cres[2][4];
; #pragma unroll
;                         for (int part = 0; part < 2; ++part) {
;                             const f32x2 w0 = (f32x2){W[part][0][2 * ep], W[part][0][2 * ep + 1]}, w1 = (f32x2){W[part][1][2 * ep], W[part][1][2 * ep + 1]};
;                             const f32x2 w2 = (f32x2){W[part][2][2 * ep], W[part][2][2 * ep + 1]}, bb = (f32x2){W[part][3][2 * ep], W[part][3][2 * ep + 1]};
;                             const f32x2 w0a = w0 * n0, w0b = w0 * m0, w2a = w2 * n15, w2b = w2 * m15;
;                             f32x2 X[4], R[4], L[4];
; #pragma unroll
;                             for (int m = 0; m < 4; ++m) { X[m] = (f32x2){acc[ai][part][m][n][2 * ep], acc[ai][part][m][n][2 * ep + 1]};
;                                 R[m] = (f32x2){dpp_prev(X[m].x), dpp_prev(X[m].y)}; L[m] = (f32x2){dpp_next(X[m].x), dpp_next(X[m].y)}; }
; #pragma unroll
;                             for (int m = 0; m < 4; ++m) {
;                                 f32x2 c = X[m] * w1 + bb; c = R[m] * w0a + c; c = L[m] * w2a + c;
;                                 if (m > 0) c = R[m > 0 ? m - 1 : 0] * w0b + c;
;                                 if (m < 3) c = L[m < 3 ? m + 1 : 3] * w2b + c;
;                                 cres[part][m] = c;
;                             }
;                             pe[0][part][n * 2 + ep] = cvt_pk_bf16(cres[part][0].x, cres[part][0].y);
;                             pe[1][part][n * 2 + ep] = cvt_pk_bf16(cres[part][3].x, cres[part][3].y);
;                             __builtin_amdgcn_sched_barrier(0);
;                         }
; #pragma unroll
;                         for (int m = 0; m < 4; ++m) {
;                             const f32x2 a = cres[0][m], v = cres[1][m];
;                             const f32x2 t = (a * a) * (-0.10294324f) + (-2.3022082f), z = a * t;
;                             f32x2 d; d.x = __builtin_amdgcn_exp2f(z.x) + 1.f; d.y = __builtin_amdgcn_exp2f(z.y) + 1.f;
;                             f32x2 r; r.x = __builtin_amdgcn_rcpf(d.x); r.y = __builtin_amdgcn_rcpf(d.y);
;                             const f32x2 o = (a * v) * r;
;                             gq[m][n * 2 + ep] = cvt_pk_bf16(o.x, o.y);
	v_pk_fma_f32 v[234:235], v[66:67], v[206:207], v[214:215]
	v_pk_fma_f32 v[236:237], v[38:39], v[206:207], v[214:215]
	v_pk_fma_f32 v[238:239], v[22:23], v[206:207], v[214:215]
	v_pk_fma_f32 v[240:241], v[6:7], v[206:207], v[214:215]
	v_pk_fma_f32 v[236:237], v[66:67], v[202:203], v[236:237]
	v_pk_fma_f32 v[238:239], v[38:39], v[202:203], v[238:239]
	v_pk_fma_f32 v[240:241], v[22:23], v[202:203], v[240:241]
	v_fmac_f32_dpp v234, v6, v202 row_shr:1 row_mask:0xf bank_mask:0xf bound_ctrl:1
	v_fmac_f32_dpp v235, v7, v203 row_shr:1 row_mask:0xf bank_mask:0xf bound_ctrl:1
	v_pk_fma_f32 v[236:237], v[22:23], v[210:211], v[236:237]
	v_pk_fma_f32 v[238:239], v[6:7], v[210:211], v[238:239]
	v_pk_fma_f32 v[234:235], v[38:39], v[210:211], v[234:235]
	v_fmac_f32_dpp v240, v66, v210 row_shl:1 row_mask:0xf bank_mask:0xf bound_ctrl:1
	v_fmac_f32_dpp v241, v67, v211 row_shl:1 row_mask:0xf bank_mask:0xf bound_ctrl:1
	v_cvt_pk_bf16_f32 v185, v234, v235
	v_cvt_pk_bf16_f32 v193, v240, v241
	v_pk_fma_f32 v[242:243], v[78:79], v[208:209], v[216:217]
	v_pk_fma_f32 v[244:245], v[46:47], v[208:209], v[216:217]
	v_pk_fma_f32 v[246:247], v[30:31], v[208:209], v[216:217]
	v_pk_fma_f32 v[248:249], v[14:15], v[208:209], v[216:217]
	v_pk_fma_f32 v[244:245], v[78:79], v[204:205], v[244:245]
	v_pk_fma_f32 v[246:247], v[46:47], v[204:205], v[246:247]
	v_pk_fma_f32 v[248:249], v[30:31], v[204:205], v[248:249]
	v_fmac_f32_dpp v242, v14, v204 row_shr:1 row_mask:0xf bank_mask:0xf bound_ctrl:1
	v_fmac_f32_dpp v243, v15, v205 row_shr:1 row_mask:0xf bank_mask:0xf bound_ctrl:1
	v_pk_fma_f32 v[244:245], v[30:31], v[212:213], v[244:245]
	v_pk_fma_f32 v[246:247], v[14:15], v[212:213], v[246:247]
	v_pk_fma_f32 v[242:243], v[46:47], v[212:213], v[242:243]
	v_fmac_f32_dpp v248, v78, v212 row_shl:1 row_mask:0xf bank_mask:0xf bound_ctrl:1
	v_fmac_f32_dpp v249, v79, v213 row_shl:1 row_mask:0xf bank_mask:0xf bound_ctrl:1
	v_cvt_pk_bf16_f32 v189, v242, v243
	v_cvt_pk_bf16_f32 v155, v248, v249
	ds_read_b64 v[202:203], v132 offset:16
	ds_read_b64 v[204:205], v132 offset:144
	ds_read_b64 v[206:207], v132 offset:272
	ds_read_b64 v[208:209], v132 offset:400
	ds_read_b64 v[210:211], v132 offset:528
	ds_read_b64 v[212:213], v132 offset:656
	ds_read_b64 v[214:215], v132 offset:784
	ds_read_b64 v[216:217], v132 offset:912
	v_pk_mul_f32 v[138:139], v[234:235], v[234:235]
	v_pk_mul_f32 v[140:141], v[236:237], v[236:237]
	v_pk_mul_f32 v[142:143], v[238:239], v[238:239]
	v_pk_mul_f32 v[144:145], v[240:241], v[240:241]
	v_pk_fma_f32 v[138:139], v[138:139], v[134:135], v[136:137]
	v_pk_fma_f32 v[140:141], v[140:141], v[134:135], v[136:137]
	v_pk_fma_f32 v[142:143], v[142:143], v[134:135], v[136:137]
	v_pk_fma_f32 v[144:145], v[144:145], v[134:135], v[136:137]
	v_pk_mul_f32 v[138:139], v[234:235], v[138:139]
	v_pk_mul_f32 v[140:141], v[236:237], v[140:141]
	v_pk_mul_f32 v[142:143], v[238:239], v[142:143]
	v_pk_mul_f32 v[144:145], v[240:241], v[144:145]
	v_exp_f32_e32 v138, v138
	v_exp_f32_e32 v139, v139
	v_exp_f32_e32 v140, v140
	v_exp_f32_e32 v141, v141
	v_exp_f32_e32 v142, v142
	v_exp_f32_e32 v143, v143
	v_exp_f32_e32 v144, v144
	v_exp_f32_e32 v145, v145
	v_pk_mul_f32 v[146:147], v[234:235], v[242:243]
	v_pk_mul_f32 v[148:149], v[236:237], v[244:245]
	v_pk_mul_f32 v[150:151], v[238:239], v[246:247]
	v_pk_mul_f32 v[152:153], v[240:241], v[248:249]
	v_pk_add_f32 v[138:139], v[138:139], 1.0 op_sel_hi:[1,0]
	v_pk_add_f32 v[140:141], v[140:141], 1.0 op_sel_hi:[1,0]
	v_pk_add_f32 v[142:143], v[142:143], 1.0 op_sel_hi:[1,0]
	v_pk_add_f32 v[144:145], v[144:145], 1.0 op_sel_hi:[1,0]
	v_rcp_f32_e32 v138, v138
	v_rcp_f32_e32 v139, v139
	v_rcp_f32_e32 v140, v140
	v_rcp_f32_e32 v141, v141
	v_rcp_f32_e32 v142, v142
	v_rcp_f32_e32 v143, v143
	v_rcp_f32_e32 v144, v144
	v_rcp_f32_e32 v145, v145
	v_pk_mul_f32 v[146:147], v[146:147], v[138:139]
	v_pk_mul_f32 v[148:149], v[148:149], v[140:141]
	v_pk_mul_f32 v[150:151], v[150:151], v[142:143]
	v_pk_mul_f32 v[152:153], v[152:153], v[144:145]
	v_cvt_pk_bf16_f32 v219, v146, v147
	v_cvt_pk_bf16_f32 v223, v148, v149
	v_cvt_pk_bf16_f32 v227, v150, v151
	v_cvt_pk_bf16_f32 v231, v152, v153
	s_waitcnt lgkmcnt(0)
	v_pk_fma_f32 v[234:235], v[56:57], v[206:207], v[214:215]
	v_pk_fma_f32 v[236:237], v[32:33], v[206:207], v[214:215]
	v_pk_fma_f32 v[238:239], v[16:17], v[206:207], v[214:215]
	v_pk_fma_f32 v[240:241], v[0:1], v[206:207], v[214:215]
	v_pk_fma_f32 v[236:237], v[56:57], v[202:203], v[236:237]
	v_pk_fma_f32 v[238:239], v[32:33], v[202:203], v[238:239]
	v_pk_fma_f32 v[240:241], v[16:17], v[202:203], v[240:241]
	v_fmac_f32_dpp v234, v0, v202 row_shr:1 row_mask:0xf bank_mask:0xf bound_ctrl:1
	v_fmac_f32_dpp v235, v1, v203 row_shr:1 row_mask:0xf bank_mask:0xf bound_ctrl:1
	v_pk_fma_f32 v[236:237], v[16:17], v[210:211], v[236:237]
	v_pk_fma_f32 v[238:239], v[0:1], v[210:211], v[238:239]
	v_pk_fma_f32 v[234:235], v[32:33], v[210:211], v[234:235]
	v_fmac_f32_dpp v240, v56, v210 row_shl:1 row_mask:0xf bank_mask:0xf bound_ctrl:1
	v_fmac_f32_dpp v241, v57, v211 row_shl:1 row_mask:0xf bank_mask:0xf bound_ctrl:1
	v_cvt_pk_bf16_f32 v186, v234, v235
	v_cvt_pk_bf16_f32 v194, v240, v241
	v_pk_fma_f32 v[242:243], v[72:73], v[208:209], v[216:217]
	v_pk_fma_f32 v[244:245], v[40:41], v[208:209], v[216:217]
	v_pk_fma_f32 v[246:247], v[24:25], v[208:209], v[216:217]
	v_pk_fma_f32 v[248:249], v[8:9], v[208:209], v[216:217]
	v_pk_fma_f32 v[244:245], v[72:73], v[204:205], v[244:245]
	v_pk_fma_f32 v[246:247], v[40:41], v[204:205], v[246:247]
	v_pk_fma_f32 v[248:249], v[24:25], v[204:205], v[248:249]
	v_fmac_f32_dpp v242, v8, v204 row_shr:1 row_mask:0xf bank_mask:0xf bound_ctrl:1
; #define LAS __attribute__((address_space(3)))
;     __device__ __forceinline__ void operator()(const f32x4 (&acc)[2][2][4][2], const Unit& u) const {
;     ...
;                         for (int k = 0; k < 4; ++k) W[part][k] = *(const LAS f32x4*)(wl + (k * 2 + part) * 128 + (8 * fq + 4 * n) * 4);
; #pragma unroll
;                     for (int ep = 0; ep < 2; ++ep) {
;                         f32x2 cres[2][4];
; #pragma unroll
;                         for (int part = 0; part < 2; ++part) {
;                             const f32x2 w0 = (f32x2){W[part][0][2 * ep], W[part][0][2 * ep + 1]}, w1 = (f32x2){W[part][1][2 * ep], W[part][1][2 * ep + 1]};
;                             const f32x2 w2 = (f32x2){W[part][2][2 * ep], W[part][2][2 * ep + 1]}, bb = (f32x2){W[part][3][2 * ep], W[part][3][2 * ep + 1]};
;                             const f32x2 w0a = w0 * n0, w0b = w0 * m0, w2a = w2 * n15, w2b = w2 * m15;
;                             f32x2 X[4], R[4], L[4];
; #pragma unroll
;                             for (int m = 0; m < 4; ++m) { X[m] = (f32x2){acc[ai][part][m][n][2 * ep], acc[ai][part][m][n][2 * ep + 1]};
;                                 R[m] = (f32x2){dpp_prev(X[m].x), dpp_prev(X[m].y)}; L[m] = (f32x2){dpp_next(X[m].x), dpp_next(X[m].y)}; }
; #pragma unroll
;                             for (int m = 0; m < 4; ++m) {
;                                 f32x2 c = X[m] * w1 + bb; c = R[m] * w0a + c; c = L[m] * w2a + c;
;                                 if (m > 0) c = R[m > 0 ? m - 1 : 0] * w0b + c;
;                                 if (m < 3) c = L[m < 3 ? m + 1 : 3] * w2b + c;
;                                 cres[part][m] = c;
;                             }
;                             pe[0][part][n * 2 + ep] = cvt_pk_bf16(cres[part][0].x, cres[part][0].y);
;                             pe[1][part][n * 2 + ep] = cvt_pk_bf16(cres[part][3].x, cres[part][3].y);
;                             __builtin_amdgcn_sched_barrier(0);
;                         }
; #pragma unroll
;                         for (int m = 0; m < 4; ++m) {
;                             const f32x2 a = cres[0][m], v = cres[1][m];
;                             const f32x2 t = (a * a) * (-0.10294324f) + (-2.3022082f), z = a * t;
;                             f32x2 d; d.x = __builtin_amdgcn_exp2f(z.x) + 1.f; d.y = __builtin_amdgcn_exp2f(z.y) + 1.f;
	v_fmac_f32_dpp v243, v9, v205 row_shr:1 row_mask:0xf bank_mask:0xf bound_ctrl:1
	v_pk_fma_f32 v[244:245], v[24:25], v[212:213], v[244:245]
	v_pk_fma_f32 v[246:247], v[8:9], v[212:213], v[246:247]
	v_pk_fma_f32 v[242:243], v[40:41], v[212:213], v[242:243]
	v_fmac_f32_dpp v248, v72, v212 row_shl:1 row_mask:0xf bank_mask:0xf bound_ctrl:1
	v_fmac_f32_dpp v249, v73, v213 row_shl:1 row_mask:0xf bank_mask:0xf bound_ctrl:1
	v_cvt_pk_bf16_f32 v190, v242, v243
	v_cvt_pk_bf16_f32 v156, v248, v249
	ds_read_b64 v[202:203], v132 offset:24
	ds_read_b64 v[204:205], v132 offset:152
	ds_read_b64 v[206:207], v132 offset:280
	ds_read_b64 v[208:209], v132 offset:408
	ds_read_b64 v[210:211], v132 offset:536
	ds_read_b64 v[212:213], v132 offset:664
	ds_read_b64 v[214:215], v132 offset:792
	ds_read_b64 v[216:217], v132 offset:920
	v_pk_mul_f32 v[138:139], v[234:235], v[234:235]
	v_pk_mul_f32 v[140:141], v[236:237], v[236:237]
	v_pk_mul_f32 v[142:143], v[238:239], v[238:239]
	v_pk_mul_f32 v[144:145], v[240:241], v[240:241]
	v_pk_fma_f32 v[138:139], v[138:139], v[134:135], v[136:137]
	v_pk_fma_f32 v[140:141], v[140:141], v[134:135], v[136:137]
	v_pk_fma_f32 v[142:143], v[142:143], v[134:135], v[136:137]
	v_pk_fma_f32 v[144:145], v[144:145], v[134:135], v[136:137]
	v_pk_mul_f32 v[138:139], v[234:235], v[138:139]
	v_pk_mul_f32 v[140:141], v[236:237], v[140:141]
	v_pk_mul_f32 v[142:143], v[238:239], v[142:143]
	v_pk_mul_f32 v[144:145], v[240:241], v[144:145]
	v_exp_f32_e32 v138, v138
	v_exp_f32_e32 v139, v139
	v_exp_f32_e32 v140, v140
	v_exp_f32_e32 v141, v141
	v_exp_f32_e32 v142, v142
	v_exp_f32_e32 v143, v143
	v_exp_f32_e32 v144, v144
	v_exp_f32_e32 v145, v145
	v_pk_mul_f32 v[146:147], v[234:235], v[242:243]
	v_pk_mul_f32 v[148:149], v[236:237], v[244:245]
	v_pk_mul_f32 v[150:151], v[238:239], v[246:247]
	v_pk_mul_f32 v[152:153], v[240:241], v[248:249]
	v_pk_add_f32 v[138:139], v[138:139], 1.0 op_sel_hi:[1,0]
	v_pk_add_f32 v[140:141], v[140:141], 1.0 op_sel_hi:[1,0]
	v_pk_add_f32 v[142:143], v[142:143], 1.0 op_sel_hi:[1,0]
	v_pk_add_f32 v[144:145], v[144:145], 1.0 op_sel_hi:[1,0]
	v_rcp_f32_e32 v138, v138
	v_rcp_f32_e32 v139, v139
	v_rcp_f32_e32 v140, v140
	v_rcp_f32_e32 v141, v141
	v_rcp_f32_e32 v142, v142
	v_rcp_f32_e32 v143, v143
	v_rcp_f32_e32 v144, v144
	v_rcp_f32_e32 v145, v145
	v_pk_mul_f32 v[146:147], v[146:147], v[138:139]
	v_pk_mul_f32 v[148:149], v[148:149], v[140:141]
	v_pk_mul_f32 v[150:151], v[150:151], v[142:143]
	v_pk_mul_f32 v[152:153], v[152:153], v[144:145]
	v_cvt_pk_bf16_f32 v220, v146, v147
	v_cvt_pk_bf16_f32 v224, v148, v149
	v_cvt_pk_bf16_f32 v228, v150, v151
	v_cvt_pk_bf16_f32 v232, v152, v153
	s_waitcnt lgkmcnt(0)
;     __device__ __forceinline__ void operator()(const f32x4 (&acc)[2][2][4][2], const Unit& u) const {
;     ...
;                             for (int m = 0; m < 4; ++m) { X[m] = (f32x2){acc[ai][part][m][n][2 * ep], acc[ai][part][m][n][2 * ep + 1]};
;                                 R[m] = (f32x2){dpp_prev(X[m].x), dpp_prev(X[m].y)}; L[m] = (f32x2){dpp_next(X[m].x), dpp_next(X[m].y)}; }
; #pragma unroll
;                             for (int m = 0; m < 4; ++m) {
;                                 f32x2 c = X[m] * w1 + bb; c = R[m] * w0a + c; c = L[m] * w2a + c;
;                                 if (m > 0) c = R[m > 0 ? m - 1 : 0] * w0b + c;
;                                 if (m < 3) c = L[m < 3 ? m + 1 : 3] * w2b + c;
;                                 cres[part][m] = c;
;                             }
;                             pe[0][part][n * 2 + ep] = cvt_pk_bf16(cres[part][0].x, cres[part][0].y);
;                             pe[1][part][n * 2 + ep] = cvt_pk_bf16(cres[part][3].x, cres[part][3].y);
;                             __builtin_amdgcn_sched_barrier(0);
;                         }
; #pragma unroll
;                         for (int m = 0; m < 4; ++m) {
;                             const f32x2 a = cres[0][m], v = cres[1][m];
;                             const f32x2 t = (a * a) * (-0.10294324f) + (-2.3022082f), z = a * t;
;                             f32x2 d; d.x = __builtin_amdgcn_exp2f(z.x) + 1.f; d.y = __builtin_amdgcn_exp2f(z.y) + 1.f;
;                             f32x2 r; r.x = __builtin_amdgcn_rcpf(d.x); r.y = __builtin_amdgcn_rcpf(d.y);
;                             const f32x2 o = (a * v) * r;
;                             gq[m][n * 2 + ep] = cvt_pk_bf16(o.x, o.y);
;                         }
;                         __builtin_amdgcn_sched_barrier(0);
;                     }
;                 }
;                 if (fr == 0 || fr == 15) {
;                     const bool sel = fr == 15;
;                     bf16_t* ep_ = eb + (unsigned)((((q * 2 + (sel ? 1 : 0)) * 352 + (ch0 >> 3)) * 4) * 8);
; #pragma unroll
;                     for (int part = 0; part < 2; ++part) {
;                         float rw[8];
; #pragma unroll
;                         for (int e = 0; e < 8; ++e) rw[e] = sel ? acc[ai][part][3][e >> 2][e & 3] : acc[ai][part][0][e >> 2][e & 3];
;                         *(u32x4*)(ep_ + part * 8) = pack8(rw);
	v_pk_fma_f32 v[234:235], v[58:59], v[206:207], v[214:215]
	v_pk_fma_f32 v[236:237], v[34:35], v[206:207], v[214:215]
	v_pk_fma_f32 v[238:239], v[18:19], v[206:207], v[214:215]
	v_pk_fma_f32 v[240:241], v[2:3], v[206:207], v[214:215]
	v_pk_fma_f32 v[236:237], v[58:59], v[202:203], v[236:237]
	v_pk_fma_f32 v[238:239], v[34:35], v[202:203], v[238:239]
	v_pk_fma_f32 v[240:241], v[18:19], v[202:203], v[240:241]
	v_fmac_f32_dpp v234, v2, v202 row_shr:1 row_mask:0xf bank_mask:0xf bound_ctrl:1
	v_fmac_f32_dpp v235, v3, v203 row_shr:1 row_mask:0xf bank_mask:0xf bound_ctrl:1
	v_pk_fma_f32 v[236:237], v[18:19], v[210:211], v[236:237]
	v_pk_fma_f32 v[238:239], v[2:3], v[210:211], v[238:239]
	v_pk_fma_f32 v[234:235], v[34:35], v[210:211], v[234:235]
	v_fmac_f32_dpp v240, v58, v210 row_shl:1 row_mask:0xf bank_mask:0xf bound_ctrl:1
	v_fmac_f32_dpp v241, v59, v211 row_shl:1 row_mask:0xf bank_mask:0xf bound_ctrl:1
	v_cvt_pk_bf16_f32 v187, v234, v235
	v_cvt_pk_bf16_f32 v195, v240, v241
	v_pk_fma_f32 v[242:243], v[74:75], v[208:209], v[216:217]
	v_pk_fma_f32 v[244:245], v[42:43], v[208:209], v[216:217]
	v_pk_fma_f32 v[246:247], v[26:27], v[208:209], v[216:217]
	v_pk_fma_f32 v[248:249], v[10:11], v[208:209], v[216:217]
	v_pk_fma_f32 v[244:245], v[74:75], v[204:205], v[244:245]
	v_pk_fma_f32 v[246:247], v[42:43], v[204:205], v[246:247]
	v_pk_fma_f32 v[248:249], v[26:27], v[204:205], v[248:249]
	v_fmac_f32_dpp v242, v10, v204 row_shr:1 row_mask:0xf bank_mask:0xf bound_ctrl:1
	v_fmac_f32_dpp v243, v11, v205 row_shr:1 row_mask:0xf bank_mask:0xf bound_ctrl:1
	v_pk_fma_f32 v[244:245], v[26:27], v[212:213], v[244:245]
	v_pk_fma_f32 v[246:247], v[10:11], v[212:213], v[246:247]
	v_pk_fma_f32 v[242:243], v[42:43], v[212:213], v[242:243]
	v_fmac_f32_dpp v248, v74, v212 row_shl:1 row_mask:0xf bank_mask:0xf bound_ctrl:1
	v_fmac_f32_dpp v249, v75, v213 row_shl:1 row_mask:0xf bank_mask:0xf bound_ctrl:1
	v_cvt_pk_bf16_f32 v191, v242, v243
	v_cvt_pk_bf16_f32 v157, v248, v249
	v_pk_mul_f32 v[138:139], v[234:235], v[234:235]
	v_pk_mul_f32 v[140:141], v[236:237], v[236:237]
	v_pk_mul_f32 v[142:143], v[238:239], v[238:239]
	v_pk_mul_f32 v[144:145], v[240:241], v[240:241]
	v_pk_fma_f32 v[138:139], v[138:139], v[134:135], v[136:137]
	v_pk_fma_f32 v[140:141], v[140:141], v[134:135], v[136:137]
	v_pk_fma_f32 v[142:143], v[142:143], v[134:135], v[136:137]
	v_pk_fma_f32 v[144:145], v[144:145], v[134:135], v[136:137]
	v_pk_mul_f32 v[138:139], v[234:235], v[138:139]
	v_pk_mul_f32 v[140:141], v[236:237], v[140:141]
	v_pk_mul_f32 v[142:143], v[238:239], v[142:143]
	v_pk_mul_f32 v[144:145], v[240:241], v[144:145]
	v_exp_f32_e32 v138, v138
	v_exp_f32_e32 v139, v139
	v_exp_f32_e32 v140, v140
	v_exp_f32_e32 v141, v141
	v_exp_f32_e32 v142, v142
	v_exp_f32_e32 v143, v143
	v_exp_f32_e32 v144, v144
	v_exp_f32_e32 v145, v145
	v_pk_mul_f32 v[146:147], v[234:235], v[242:243]
	v_pk_mul_f32 v[148:149], v[236:237], v[244:245]
	v_pk_mul_f32 v[150:151], v[238:239], v[246:247]
	v_pk_mul_f32 v[152:153], v[240:241], v[248:249]
	v_pk_add_f32 v[138:139], v[138:139], 1.0 op_sel_hi:[1,0]
	v_pk_add_f32 v[140:141], v[140:141], 1.0 op_sel_hi:[1,0]
	v_pk_add_f32 v[142:143], v[142:143], 1.0 op_sel_hi:[1,0]
	v_pk_add_f32 v[144:145], v[144:145], 1.0 op_sel_hi:[1,0]
	v_rcp_f32_e32 v138, v138
	v_rcp_f32_e32 v139, v139
	v_rcp_f32_e32 v140, v140
	v_rcp_f32_e32 v141, v141
	v_rcp_f32_e32 v142, v142
	v_rcp_f32_e32 v143, v143
	v_rcp_f32_e32 v144, v144
	v_rcp_f32_e32 v145, v145
	v_pk_mul_f32 v[146:147], v[146:147], v[138:139]
	v_pk_mul_f32 v[148:149], v[148:149], v[140:141]
	v_pk_mul_f32 v[150:151], v[150:151], v[142:143]
	v_pk_mul_f32 v[152:153], v[152:153], v[144:145]
	v_cvt_pk_bf16_f32 v221, v146, v147
	v_cvt_pk_bf16_f32 v225, v148, v149
	v_cvt_pk_bf16_f32 v229, v150, v151
	v_cvt_pk_bf16_f32 v233, v152, v153
	s_mov_b64 s[22:23], exec
	s_mov_b64 exec, s[6:7]
	v_cvt_pk_bf16_f32 v138, v64, v65
	v_cvt_pk_bf16_f32 v139, v66, v67
	v_cvt_pk_bf16_f32 v140, v56, v57
	v_cvt_pk_bf16_f32 v141, v58, v59
	v_cvt_pk_bf16_f32 v142, v76, v77
	v_cvt_pk_bf16_f32 v143, v78, v79
	v_cvt_pk_bf16_f32 v144, v72, v73
	v_cvt_pk_bf16_f32 v145, v74, v75
	global_store_dwordx4 v129, v[138:141], s[10:11]
	global_store_dwordx4 v129, v[142:145], s[10:11] offset:16
	global_store_dwordx4 v129, v[184:187], s[10:11] offset:32
	global_store_dwordx4 v129, v[188:191], s[10:11] offset:48
	s_mov_b64 exec, s[8:9]
	v_cvt_pk_bf16_f32 v146, v4, v5
	v_cvt_pk_bf16_f32 v147, v6, v7
	v_cvt_pk_bf16_f32 v148, v0, v1
	v_cvt_pk_bf16_f32 v149, v2, v3
	v_cvt_pk_bf16_f32 v150, v12, v13
	v_cvt_pk_bf16_f32 v151, v14, v15
	v_cvt_pk_bf16_f32 v152, v8, v9
	v_cvt_pk_bf16_f32 v153, v10, v11
	global_store_dwordx4 v162, v[146:149], s[10:11]
	global_store_dwordx4 v162, v[150:153], s[10:11] offset:16
	global_store_dwordx4 v162, v[192:195], s[10:11] offset:32
	global_store_dwordx4 v162, v[154:157], s[10:11] offset:48
	s_mov_b64 exec, s[56:57]
	global_store_dwordx4 v128, v[218:221], s[52:53]
	s_mov_b64 exec, s[22:23]
	v_add_u32_e32 v133, 0x1600, v128
	v_add_u32_e32 v130, 0x2c00, v128
	v_add_u32_e32 v131, 0x4200, v128
	global_store_dwordx4 v133, v[222:225], s[52:53]
	global_store_dwordx4 v130, v[226:229], s[52:53]
	s_mov_b64 exec, s[58:59]
	global_store_dwordx4 v131, v[230:233], s[52:53]
	s_mov_b64 exec, s[22:23]
	s_mov_b64 s[8:9], 0
